# NSA selected loop: umask in SGPRs with scalar ff1 search, per-lane selw words in VGPRs (no per-tile LDS lookups)
# speedup vs baseline: 1.0031x; 1.0031x over previous
.LBB0_394:
	v_lshlrev_b32_e32 v9, 16, v82
	v_lshlrev_b32_e32 v8, 16, v86
	v_mov_b32_e32 v24, v78
	v_mov_b32_e32 v25, v74
	v_pk_mul_f32 v[24:25], v[24:25], v[8:9]
	v_and_b32_e32 v11, 0xffff0000, v82
	v_sub_f32_e32 v0, v24, v25
	v_mov_b32_e32 v24, v74
	v_mov_b32_e32 v25, v78
	v_and_b32_e32 v10, 0xffff0000, v86
	v_pk_mul_f32 v[8:9], v[24:25], v[8:9]
	v_mov_b32_e32 v74, v79
	v_add_f32_e32 v5, v8, v9
	v_cmp_gt_u32_e32 vcc, 32, v185
	v_pk_mul_f32 v[8:9], v[74:75], v[10:11]
	v_mov_b32_e32 v78, v75
	v_cndmask_b32_e32 v0, v5, v0, vcc
	v_sub_f32_e32 v5, v8, v9
	v_pk_mul_f32 v[8:9], v[78:79], v[10:11]
	v_lshlrev_b32_e32 v13, 16, v83
	v_lshlrev_b32_e32 v12, 16, v87
	v_add_f32_e32 v7, v9, v8
	v_mov_b32_e32 v8, v80
	v_mov_b32_e32 v9, v76
	v_pk_mul_f32 v[8:9], v[8:9], v[12:13]
	v_cndmask_b32_e32 v5, v7, v5, vcc
	v_sub_f32_e32 v7, v8, v9
	v_mov_b32_e32 v8, v76
	v_mov_b32_e32 v9, v80
	v_pk_mul_f32 v[8:9], v[8:9], v[12:13]
	v_and_b32_e32 v15, 0xffff0000, v83
	v_and_b32_e32 v14, 0xffff0000, v87
	v_add_f32_e32 v8, v9, v8
	v_mov_b32_e32 v76, v81
	v_cndmask_b32_e32 v7, v8, v7, vcc
	v_pk_mul_f32 v[8:9], v[76:77], v[14:15]
	v_mov_b32_e32 v80, v77
	v_sub_f32_e32 v10, v8, v9
	v_pk_mul_f32 v[8:9], v[80:81], v[14:15]
	v_lshlrev_b32_e32 v17, 16, v84
	v_add_f32_e32 v8, v9, v8
	v_lshlrev_b32_e32 v16, 16, v88
	v_cndmask_b32_e32 v10, v8, v10, vcc
	v_mov_b32_e32 v8, v70
	v_mov_b32_e32 v9, v66
	v_pk_mul_f32 v[8:9], v[8:9], v[16:17]
	v_and_b32_e32 v19, 0xffff0000, v84
	v_sub_f32_e32 v11, v8, v9
	v_mov_b32_e32 v8, v66
	v_mov_b32_e32 v9, v70
	v_pk_mul_f32 v[8:9], v[8:9], v[16:17]
	v_and_b32_e32 v18, 0xffff0000, v88
	v_add_f32_e32 v8, v9, v8
	v_mov_b32_e32 v66, v71
	v_cndmask_b32_e32 v11, v8, v11, vcc
	v_pk_mul_f32 v[8:9], v[66:67], v[18:19]
	v_mov_b32_e32 v70, v67
	v_sub_f32_e32 v12, v8, v9
	v_pk_mul_f32 v[8:9], v[70:71], v[18:19]
	v_lshlrev_b32_e32 v21, 16, v85
	v_add_f32_e32 v8, v9, v8
	v_lshlrev_b32_e32 v20, 16, v89
	v_cndmask_b32_e32 v12, v8, v12, vcc
	v_mov_b32_e32 v8, v72
	v_mov_b32_e32 v9, v68
	v_pk_mul_f32 v[8:9], v[8:9], v[20:21]
	v_and_b32_e32 v23, 0xffff0000, v85
	v_sub_f32_e32 v13, v8, v9
	v_mov_b32_e32 v8, v68
	v_mov_b32_e32 v9, v72
	v_pk_mul_f32 v[8:9], v[8:9], v[20:21]
	v_and_b32_e32 v22, 0xffff0000, v89
	v_add_f32_e32 v8, v9, v8
	v_mov_b32_e32 v68, v73
	v_cndmask_b32_e32 v13, v8, v13, vcc
	v_pk_mul_f32 v[8:9], v[68:69], v[22:23]
	v_mov_b32_e32 v72, v69
	v_sub_f32_e32 v14, v8, v9
	v_pk_mul_f32 v[8:9], v[72:73], v[22:23]
	s_lshl_b32 s46, s75, 3
	v_add_f32_e32 v8, v9, v8
	s_add_i32 s46, s46, s74
	v_cndmask_b32_e32 v8, v8, v14, vcc
	v_mov_b32_e32 v81, 0
	v_cvt_pk_bf16_f32 v142, v0, v5
	v_cvt_pk_bf16_f32 v143, v7, v10
	v_cvt_pk_bf16_f32 v144, v11, v12
	v_cvt_pk_bf16_f32 v145, v13, v8
	s_cmp_gt_u32 s94, s80
	v_mov_b32_e32 v80, v81
	v_mov_b32_e32 v79, v81
	v_mov_b32_e32 v78, v81
	v_mov_b32_e32 v77, v81
	v_mov_b32_e32 v76, v81
	v_mov_b32_e32 v75, v81
	v_mov_b32_e32 v74, v81
	v_mov_b32_e32 v73, v81
	v_mov_b32_e32 v72, v81
	v_mov_b32_e32 v71, v81
	v_mov_b32_e32 v70, v81
	v_mov_b32_e32 v69, v81
	v_mov_b32_e32 v68, v81
	v_mov_b32_e32 v67, v81
	v_mov_b32_e32 v66, v81
	s_waitcnt vmcnt(6)
	v_mov_b32_e32 v97, v81
	v_mov_b32_e32 v96, v81
	v_mov_b32_e32 v95, v81
	v_mov_b32_e32 v94, v81
	v_mov_b32_e32 v93, v81
	v_mov_b32_e32 v92, v81
	v_mov_b32_e32 v91, v81
	v_mov_b32_e32 v90, v81
	v_mov_b32_e32 v89, v81
	v_mov_b32_e32 v88, v81
	v_mov_b32_e32 v87, v81
	v_mov_b32_e32 v86, v81
	v_mov_b32_e32 v85, v81
	v_mov_b32_e32 v84, v81
	v_mov_b32_e32 v83, v81
	v_mov_b32_e32 v82, v81
	v_mov_b32_e32 v201, v81
	s_cbranch_scc1 .LBB0_410
	v_lshrrev_b32_e32 v5, 3, v6
	v_lshlrev_b32_e32 v166, 4, v6
	v_and_b32_e32 v168, 4, v5
	v_ashrrev_i32_e32 v5, 31, v4
	v_mov_b32_e32 v201, 0
	v_lshlrev_b32_e32 v0, 4, v184
	ds_read_b128 v[226:229], v0 offset:49152
	ds_read_b128 v[230:233], v1 offset:49664
	s_waitcnt lgkmcnt(0)
	v_readfirstlane_b32 s2, v230
	v_readfirstlane_b32 s3, v231
	v_readfirstlane_b32 s98, v232
	v_readfirstlane_b32 s99, v233
	v_and_b32_e32 v167, 0x3f0, v166
	s_mov_b32 s49, 0
	v_mov_b32_e32 v170, 0xf149f2ca
	v_lshlrev_b64 v[162:163], 1, v[2:3]
	v_lshlrev_b64 v[164:165], 1, v[4:5]
	v_mov_b32_e32 v82, 0
	v_mov_b32_e32 v83, v201
	v_mov_b32_e32 v84, v201
	v_mov_b32_e32 v85, v201
	v_mov_b32_e32 v86, v201
	v_mov_b32_e32 v87, v201
	v_mov_b32_e32 v88, v201
	v_mov_b32_e32 v89, v201
	v_mov_b32_e32 v90, v201
	v_mov_b32_e32 v91, v201
	v_mov_b32_e32 v92, v201
	v_mov_b32_e32 v93, v201
	v_mov_b32_e32 v94, v201
	v_mov_b32_e32 v95, v201
	v_mov_b32_e32 v96, v201
	v_mov_b32_e32 v97, v201
	v_mov_b32_e32 v66, v201
	v_mov_b32_e32 v67, v201
	v_mov_b32_e32 v68, v201
	v_mov_b32_e32 v69, v201
	v_mov_b32_e32 v70, v201
	v_mov_b32_e32 v71, v201
	v_mov_b32_e32 v72, v201
	v_mov_b32_e32 v73, v201
	v_mov_b32_e32 v74, v201
	v_mov_b32_e32 v75, v201
	v_mov_b32_e32 v76, v201
	v_mov_b32_e32 v77, v201
	v_mov_b32_e32 v78, v201
	v_mov_b32_e32 v79, v201
	v_mov_b32_e32 v80, v201
	v_mov_b32_e32 v81, v201
	s_waitcnt vmcnt(0)
	ds_write_b128 v166, v[98:101]
	ds_write_b128 v166, v[102:105] offset:4096
	ds_write_b128 v166, v[106:109] offset:8192
	ds_write_b128 v166, v[110:113] offset:12288
.LBB0_396:
	s_lshl_b32 s52, s49, 14
	s_add_i32 s0, s94, 1
	s_max_i32 s1, s43, s0
	s_mov_b32 s0, s94
	s_waitcnt vmcnt(0)
	s_waitcnt lgkmcnt(0)
	s_barrier
	s_add_i32 s0, s94, 1
	s_cmp_gt_i32 s0, s80
	s_cbranch_scc1 .LBB0_402
	s_cmp_lt_u32 s0, 64
	s_cbranch_scc0 .Lmy_sel_hi
	s_lshr_b64 s[12:13], s[2:3], s0
	s_cmp_lg_u64 s[12:13], 0
	s_cbranch_scc0 .Lmy_sel_hi64
	s_ff1_i32_b64 s12, s[12:13]
	s_add_i32 s0, s0, s12
	s_branch .Lmy_sel_found
.Lmy_sel_hi64:
	s_mov_b32 s0, 64
.Lmy_sel_hi:
	s_lshr_b64 s[12:13], s[98:99], s0
	s_cmp_lg_u64 s[12:13], 0
	s_cbranch_scc0 .LBB0_402
	s_ff1_i32_b64 s12, s[12:13]
	s_add_i32 s0, s0, s12
.Lmy_sel_found:
	s_ashr_i32 s1, s0, 31
	s_lshl_b64 s[12:13], s[0:1], 13
	s_add_u32 s14, s44, s12
	s_addc_u32 s15, s45, s13
	s_add_u32 s12, s47, s12
	s_addc_u32 s13, s48, s13
	v_readfirstlane_b32 s1, v166
	s_sub_u32 m0, 0x4000, s52
	s_nop 0
	s_add_u32 m0, m0, s1
	s_nop 0
	global_load_lds_dwordx4 v162, s[14:15]
	s_add_u32 m0, m0, 0x1000
	s_nop 0
	global_load_lds_dwordx4 v164, s[14:15]
	s_add_u32 m0, m0, 0x1000
	s_nop 0
	global_load_lds_dwordx4 v162, s[12:13]
	s_add_u32 m0, m0, 0x1000
	s_nop 0
	global_load_lds_dwordx4 v164, s[12:13]
	s_mov_b32 s1, s0
.LBB0_402:
	s_lshl_b32 s0, 1, s94
	s_cmp_lt_u32 s94, 64
	s_cbranch_scc0 .Lmy_w23
	s_cmp_lt_u32 s94, 32
	s_cbranch_scc0 .Lmy_w1
	v_and_b32_e32 v2, s0, v226
	s_branch .Lmy_wd
.Lmy_w1:
	v_and_b32_e32 v2, s0, v227
	s_branch .Lmy_wd
.Lmy_w23:
	s_cmp_lt_u32 s94, 0x60
	s_cbranch_scc0 .Lmy_w3
	v_and_b32_e32 v2, s0, v228
	s_branch .Lmy_wd
.Lmy_w3:
	v_and_b32_e32 v2, s0, v229
.Lmy_wd:
	v_cmp_ne_u32_e64 s[40:41], 0, v2
	s_mov_b64 vcc, s[40:41]
	s_cbranch_vccz .LBB0_408
	v_add_u32_e32 v169, s52, v167
	ds_read_b128 v[2:5], v169
	ds_read_b128 v[114:117], v169 offset:1024
	ds_read_b128 v[118:121], v169 offset:2048
	ds_read_b128 v[122:125], v169 offset:3072
	ds_read_b128 v[6:9], v169 offset:4096
	ds_read_b128 v[126:129], v169 offset:5120
	ds_read_b128 v[146:149], v169 offset:6144
	ds_read_b128 v[172:175], v169 offset:7168
	s_waitcnt lgkmcnt(7)
	v_mfma_f32_32x32x16_bf16 v[18:33], v[2:5], v[142:145], 0
	s_waitcnt lgkmcnt(3)
	v_mfma_f32_32x32x16_bf16 v[2:17], v[6:9], v[142:145], 0
	v_mfma_f32_32x32x16_bf16 v[18:33], v[114:117], v[130:133], v[18:33]
	s_waitcnt lgkmcnt(2)
	v_mfma_f32_32x32x16_bf16 v[2:17], v[126:129], v[130:133], v[2:17]
	v_mfma_f32_32x32x16_bf16 v[18:33], v[118:121], v[134:137], v[18:33]
	s_waitcnt lgkmcnt(1)
	v_mfma_f32_32x32x16_bf16 v[2:17], v[146:149], v[134:137], v[2:17]
	v_mfma_f32_32x32x16_bf16 v[18:33], v[122:125], v[138:141], v[18:33]
	ds_read_b128 v[158:161], v169 offset:8192
	ds_read_b128 v[154:157], v169 offset:9216
	ds_read_b128 v[150:153], v169 offset:10240
	ds_read_b128 v[146:149], v169 offset:11264
	ds_read_b128 v[126:129], v169 offset:12288
	ds_read_b128 v[122:125], v169 offset:13312
	ds_read_b128 v[118:121], v169 offset:14336
	ds_read_b128 v[114:117], v169 offset:15360
	s_waitcnt lgkmcnt(8)
	v_mfma_f32_32x32x16_bf16 v[2:17], v[172:175], v[138:141], v[2:17]
	s_lshl_b32 s0, s94, 6
	s_or_b32 s12, s0, 63
	s_cmp_le_i32 s12, s46
	s_cbranch_scc1 .LBB0_405
	v_or_b32_e32 v169, s0, v168
	v_or_b32_e32 v171, 32, v169
	v_cmp_le_i32_e32 vcc, v169, v200
	v_or_b32_e32 v172, 34, v169
	s_nop 0
	v_cndmask_b32_e32 v18, v222, v18, vcc
	v_cmp_le_i32_e32 vcc, v171, v200
	v_or_b32_e32 v171, 33, v169
	s_nop 0
	v_cndmask_b32_e32 v2, v222, v2, vcc
	v_cmp_lt_i32_e32 vcc, v169, v200
	s_nop 1
	v_cndmask_b32_e32 v19, v222, v19, vcc
	v_cmp_le_i32_e32 vcc, v171, v200
	v_or_b32_e32 v171, 2, v169
	s_nop 0
	v_cndmask_b32_e32 v3, v222, v3, vcc
	v_cmp_le_i32_e32 vcc, v171, v200
	v_or_b32_e32 v171, 3, v169
	s_nop 0
	v_cndmask_b32_e32 v20, v222, v20, vcc
	v_cmp_le_i32_e32 vcc, v172, v200
	v_or_b32_e32 v172, 35, v169
	s_nop 0
	v_cndmask_b32_e32 v4, v222, v4, vcc
	v_cmp_le_i32_e32 vcc, v171, v200
	v_or_b32_e32 v171, 8, v169
	s_nop 0
	v_cndmask_b32_e32 v21, v222, v21, vcc
	v_cmp_le_i32_e32 vcc, v172, v200
	v_or_b32_e32 v172, 40, v169
	s_nop 0
	v_cndmask_b32_e32 v5, v222, v5, vcc
	v_cmp_le_i32_e32 vcc, v171, v200
	v_or_b32_e32 v171, 9, v169
	s_nop 0
	v_cndmask_b32_e32 v22, v222, v22, vcc
	v_cmp_le_i32_e32 vcc, v172, v200
	v_or_b32_e32 v172, 41, v169
	s_nop 0
	v_cndmask_b32_e32 v6, v222, v6, vcc
	v_cmp_le_i32_e32 vcc, v171, v200
	v_or_b32_e32 v171, 10, v169
	s_nop 0
	v_cndmask_b32_e32 v23, v222, v23, vcc
	v_cmp_le_i32_e32 vcc, v172, v200
	v_or_b32_e32 v172, 42, v169
	s_nop 0
	v_cndmask_b32_e32 v7, v222, v7, vcc
	v_cmp_le_i32_e32 vcc, v171, v200
	v_or_b32_e32 v171, 11, v169
	s_nop 0
	v_cndmask_b32_e32 v24, v222, v24, vcc
	v_cmp_le_i32_e32 vcc, v172, v200
	v_or_b32_e32 v172, 43, v169
	s_nop 0
	v_cndmask_b32_e32 v8, v222, v8, vcc
	v_cmp_le_i32_e32 vcc, v171, v200
	v_or_b32_e32 v171, 16, v169
	s_nop 0
	v_cndmask_b32_e32 v25, v222, v25, vcc
	v_cmp_le_i32_e32 vcc, v172, v200
	v_or_b32_e32 v172, 48, v169
	s_nop 0
	v_cndmask_b32_e32 v9, v222, v9, vcc
	v_cmp_le_i32_e32 vcc, v171, v200
	v_or_b32_e32 v171, 17, v169
	s_nop 0
	v_cndmask_b32_e32 v26, v222, v26, vcc
	v_cmp_le_i32_e32 vcc, v172, v200
	v_or_b32_e32 v172, 49, v169
	s_nop 0
	v_cndmask_b32_e32 v10, v222, v10, vcc
	v_cmp_le_i32_e32 vcc, v171, v200
	v_or_b32_e32 v171, 18, v169
	s_nop 0
	v_cndmask_b32_e32 v27, v222, v27, vcc
	v_cmp_le_i32_e32 vcc, v172, v200
	v_or_b32_e32 v172, 50, v169
	s_nop 0
	v_cndmask_b32_e32 v11, v222, v11, vcc
	v_cmp_le_i32_e32 vcc, v171, v200
	v_or_b32_e32 v171, 19, v169
	s_nop 0
	v_cndmask_b32_e32 v28, v222, v28, vcc
	v_cmp_le_i32_e32 vcc, v172, v200
	v_or_b32_e32 v172, 51, v169
	s_nop 0
	v_cndmask_b32_e32 v12, v222, v12, vcc
	v_cmp_le_i32_e32 vcc, v171, v200
	v_or_b32_e32 v171, 24, v169
	s_nop 0
	v_cndmask_b32_e32 v29, v222, v29, vcc
	v_cmp_le_i32_e32 vcc, v172, v200
	v_or_b32_e32 v172, 56, v169
	s_nop 0
	v_cndmask_b32_e32 v13, v222, v13, vcc
	v_cmp_le_i32_e32 vcc, v171, v200
	v_or_b32_e32 v171, 25, v169
	s_nop 0
	v_cndmask_b32_e32 v30, v222, v30, vcc
	v_cmp_le_i32_e32 vcc, v172, v200
	v_or_b32_e32 v172, 57, v169
	s_nop 0
	v_cndmask_b32_e32 v14, v222, v14, vcc
	v_cmp_le_i32_e32 vcc, v171, v200
	v_or_b32_e32 v171, 26, v169
	s_nop 0
	v_cndmask_b32_e32 v31, v222, v31, vcc
	v_cmp_le_i32_e32 vcc, v172, v200
	v_or_b32_e32 v172, 58, v169
	s_nop 0
	v_cndmask_b32_e32 v15, v222, v15, vcc
	v_cmp_le_i32_e32 vcc, v171, v200
	v_or_b32_e32 v171, 27, v169
	v_or_b32_e32 v169, 59, v169
	v_cndmask_b32_e32 v32, v222, v32, vcc
	v_cmp_le_i32_e32 vcc, v172, v200
	s_nop 1
	v_cndmask_b32_e32 v16, v222, v16, vcc
	v_cmp_le_i32_e32 vcc, v171, v200
	s_nop 1
	v_cndmask_b32_e32 v33, v222, v33, vcc
	v_cmp_le_i32_e32 vcc, v169, v200
	s_nop 1
	v_cndmask_b32_e32 v17, v222, v17, vcc
